# norm phases P5/P10: rows 1..3 of each wave requested together during row 0 (two extra raw register sets)
# speedup vs baseline: 1.0332x; 1.0018x over previous
.Lnorm_skip_497:
	s_cmp_lg_u32 s21, 0
	s_cbranch_scc1 .Lnorm3_skip_497
	s_and_b64 s[6:7], s[16:17], exec
	s_cselect_b32 s14, s12, s14
	s_ashr_i32 s15, s14, 31
	s_lshl_b64 s[6:7], s[14:15], 12
	v_lshl_add_u64 v[2:3], v[44:45], 0, s[6:7]
	global_load_dwordx2 v[4:5], v[2:3], off
	global_load_dwordx2 v[8:9], v[2:3], off offset:512
	global_load_dwordx2 v[12:13], v[2:3], off offset:1024
	global_load_dwordx2 v[16:17], v[2:3], off offset:1536
	global_load_dwordx2 v[20:21], v[2:3], off offset:2048
	global_load_dwordx2 v[24:25], v[2:3], off offset:2560
	global_load_dwordx2 v[28:29], v[2:3], off offset:3072
	global_load_dwordx2 v[148:149], v[2:3], off offset:3584
	s_mov_b64 s[6:7], 0x1000
	v_lshl_add_u64 v[2:3], v[2:3], 0, s[6:7]
	global_load_dwordx2 v[232:233], v[2:3], off
	global_load_dwordx2 v[234:235], v[2:3], off offset:512
	global_load_dwordx2 v[236:237], v[2:3], off offset:1024
	global_load_dwordx2 v[238:239], v[2:3], off offset:1536
	global_load_dwordx2 v[240:241], v[2:3], off offset:2048
	global_load_dwordx2 v[242:243], v[2:3], off offset:2560
	global_load_dwordx2 v[244:245], v[2:3], off offset:3072
	global_load_dwordx2 v[246:247], v[2:3], off offset:3584
	v_lshl_add_u64 v[2:3], v[2:3], 0, s[6:7]
	global_load_dwordx2 v[248:249], v[2:3], off
	global_load_dwordx2 v[250:251], v[2:3], off offset:512
	global_load_dwordx2 v[252:253], v[2:3], off offset:1024
	global_load_dwordx2 v[254:255], v[2:3], off offset:1536
	global_load_dwordx2 v[150:151], v[2:3], off offset:2048
	global_load_dwordx2 v[152:153], v[2:3], off offset:2560
	global_load_dwordx2 v[154:155], v[2:3], off offset:3072
	global_load_dwordx2 v[156:157], v[2:3], off offset:3584
.Lnorm3_skip_497:
	v_mov_b32_e32 v98, v73
	v_mov_b32_e32 v99, v77
	v_mov_b32_e32 v96, v72
	v_mov_b32_e32 v97, v76
	v_pk_mul_f32 v[98:99], v[98:99], v[98:99]
	v_mov_b32_e32 v100, v75
	v_mov_b32_e32 v101, v79
	v_pk_fma_f32 v[96:97], v[96:97], v[96:97], v[98:99]
	v_mov_b32_e32 v98, v74
	v_mov_b32_e32 v99, v78
	v_pk_mul_f32 v[100:101], v[100:101], v[100:101]
	s_nop 0
	v_pk_fma_f32 v[98:99], v[98:99], v[98:99], v[100:101]
	v_pk_mul_f32 v[100:101], v[68:69], v[68:69]
	v_pk_add_f32 v[96:97], v[96:97], v[98:99]
	v_pk_mul_f32 v[98:99], v[70:71], v[70:71]
	v_pk_add_f32 v[96:97], v[96:97], v[96:97] op_sel_hi:[0,1]
	v_pk_mov_b32 v[102:103], v[100:101], v[98:99] op_sel:[1,0]
	v_mov_b32_e32 v101, v99
	v_pk_add_f32 v[98:99], v[102:103], v[100:101]
	v_mul_f32_e32 v100, v64, v64
	v_pk_fma_f32 v[100:101], v[64:65], v[64:65], v[100:101] op_sel_hi:[1,1,0]
	v_pk_add_f32 v[98:99], v[98:99], v[98:99] op_sel_hi:[0,1]
	v_mul_f32_e32 v100, v66, v66
	v_pk_fma_f32 v[102:103], v[66:67], v[66:67], v[100:101] op_sel_hi:[1,1,0]
	v_mul_f32_e32 v100, v60, v60
	v_mul_f32_e32 v102, v61, v61
	v_mul_f32_e32 v98, v62, v62
	v_mul_f32_e32 v96, v63, v63
	v_pk_add_f32 v[100:101], v[100:101], v[102:103]
	v_pk_add_f32 v[96:97], v[98:99], v[96:97]
	v_pk_mul_f32 v[98:99], v[58:59], v[58:59]
	v_pk_add_f32 v[96:97], v[100:101], v[96:97]
	v_pk_mul_f32 v[100:101], v[56:57], v[56:57]
	v_pk_add_f32 v[96:97], v[96:97], v[96:97] op_sel_hi:[0,1]
	v_pk_mov_b32 v[102:103], v[100:101], v[98:99] op_sel:[1,0]
	v_mov_b32_e32 v101, v99
	v_pk_add_f32 v[98:99], v[102:103], v[100:101]
	v_mul_f32_e32 v100, v52, v52
	v_pk_fma_f32 v[100:101], v[52:53], v[52:53], v[100:101] op_sel_hi:[1,1,0]
	v_pk_add_f32 v[98:99], v[98:99], v[98:99] op_sel_hi:[0,1]
	v_mul_f32_e32 v100, v54, v54
	v_pk_fma_f32 v[102:103], v[54:55], v[54:55], v[100:101] op_sel_hi:[1,1,0]
	v_mul_f32_e32 v100, v48, v48
	v_mul_f32_e32 v102, v49, v49
	v_mul_f32_e32 v98, v50, v50
	v_mul_f32_e32 v96, v51, v51
	v_pk_add_f32 v[100:101], v[100:101], v[102:103]
	v_pk_add_f32 v[96:97], v[98:99], v[96:97]
	s_nop 0
	v_pk_add_f32 v[96:97], v[100:101], v[96:97]
	s_nop 0
	v_add_f32_e32 v95, v96, v97
	ds_bpermute_b32 v96, v1, v95
	s_waitcnt lgkmcnt(0)
	v_add_f32_e32 v95, v95, v96
	ds_bpermute_b32 v96, v80, v95
	s_waitcnt lgkmcnt(0)
	v_add_f32_e32 v95, v95, v96
	ds_bpermute_b32 v96, v81, v95
	s_waitcnt lgkmcnt(0)
	v_add_f32_e32 v95, v95, v96
	ds_bpermute_b32 v96, v82, v95
	s_waitcnt lgkmcnt(0)
	v_add_f32_e32 v95, v95, v96
	ds_bpermute_b32 v96, v83, v95
	s_waitcnt lgkmcnt(0)
	v_add_f32_e32 v95, v95, v96
	ds_bpermute_b32 v96, v84, v95
	s_waitcnt lgkmcnt(0)
	v_add_f32_e32 v95, v95, v96
	v_fmamk_f32 v95, v95, 0x3a000000, v85
	v_mul_f32_e32 v96, 0x4f800000, v95
	v_cmp_gt_f32_e32 vcc, s38, v95
	s_nop 1
	v_cndmask_b32_e32 v95, v95, v96, vcc
	v_sqrt_f32_e32 v96, v95
	s_nop 0
	v_add_u32_e32 v97, -1, v96
	v_fma_f32 v98, -v97, v96, v95
	v_cmp_ge_f32_e64 s[6:7], 0, v98
	v_add_u32_e32 v98, 1, v96
	s_nop 0
	v_cndmask_b32_e64 v97, v96, v97, s[6:7]
	v_fma_f32 v96, -v98, v96, v95
	v_cmp_lt_f32_e64 s[6:7], 0, v96
	s_nop 1
	v_cndmask_b32_e64 v96, v97, v98, s[6:7]
	v_mul_f32_e32 v97, 0x37800000, v96
	v_cndmask_b32_e32 v96, v96, v97, vcc
	v_cmp_class_f32_e32 vcc, v95, v86
	s_nop 1
	v_cndmask_b32_e32 v95, v96, v95, vcc
	v_div_scale_f32 v96, s[6:7], v95, v95, 1.0
	v_rcp_f32_e32 v97, v96
	s_ashr_i32 s6, s12, 11
	s_mul_hi_i32 s7, s6, 0x12000
	s_mul_i32 s6, s6, 0x12000
	v_fma_f32 v98, -v96, v97, 1.0
	v_fmac_f32_e32 v97, v98, v97
	v_div_scale_f32 v98, vcc, 1.0, v95, 1.0
	v_mul_f32_e32 v99, v98, v97
	v_fma_f32 v100, -v96, v99, v98
	v_fmac_f32_e32 v99, v100, v97
	v_fma_f32 v96, -v96, v99, v98
	v_div_fmas_f32 v96, v96, v97, v99
	v_div_fixup_f32 v100, v96, v95, 1.0
	v_pk_mul_f32 v[96:97], v[78:79], v[100:101] op_sel_hi:[1,0]
	v_pk_mul_f32 v[98:99], v[76:77], v[100:101] op_sel_hi:[1,0]
	s_waitcnt vmcnt(24)
	v_mov_b64_e32 v[76:77], v[116:117]
	v_mov_b64_e32 v[78:79], v[118:119]
	s_add_u32 s6, s28, s6
	s_addc_u32 s7, s29, s7
	s_add_u32 s18, s6, 0x2000
	s_addc_u32 s19, s7, 0
	s_ashr_i32 s13, s12, 31
	s_lshl_b64 s[12:13], s[12:13], 12
	s_add_i32 s31, s31, s22
	s_add_i32 s21, s21, 1
	s_and_b64 vcc, exec, s[16:17]
	s_waitcnt vmcnt(24)
	v_pk_mul_f32 v[102:103], v[76:77], v[98:99]
	v_pk_mul_f32 v[104:105], v[78:79], v[96:97]
	v_mov_b64_e32 v[76:77], v[120:121]
	v_mov_b64_e32 v[78:79], v[122:123]
	v_mov_b64_e32 v[96:97], v[124:125]
	v_mov_b64_e32 v[98:99], v[126:127]
	v_pk_add_f32 v[78:79], v[78:79], 1.0 op_sel_hi:[1,0]
	v_pk_add_f32 v[76:77], v[76:77], 1.0 op_sel_hi:[1,0]
	v_pk_fma_f32 v[78:79], v[78:79], v[104:105], v[98:99]
	v_pk_fma_f32 v[76:77], v[76:77], v[102:103], v[96:97]
	v_lshl_add_u64 v[96:97], v[46:47], 0, s[12:13]
	v_cvt_pk_bf16_f32 v76, v76, v77
	v_cvt_pk_bf16_f32 v77, v78, v79
	global_store_dwordx2 v[96:97], v[76:77], off
	v_pk_mul_f32 v[76:77], v[74:75], v[100:101] op_sel_hi:[1,0]
	v_pk_mul_f32 v[78:79], v[72:73], v[100:101] op_sel_hi:[1,0]
	v_mov_b64_e32 v[72:73], v[128:129]
	v_mov_b64_e32 v[74:75], v[130:131]
	s_mov_b32 s12, s14
	v_pk_mul_f32 v[98:99], v[72:73], v[78:79]
	v_pk_mul_f32 v[102:103], v[74:75], v[76:77]
	v_mov_b64_e32 v[72:73], v[132:133]
	v_mov_b64_e32 v[74:75], v[134:135]
	v_mov_b64_e32 v[76:77], v[136:137]
	v_mov_b64_e32 v[78:79], v[138:139]
	v_pk_add_f32 v[74:75], v[74:75], 1.0 op_sel_hi:[1,0]
	v_pk_add_f32 v[72:73], v[72:73], 1.0 op_sel_hi:[1,0]
	v_pk_fma_f32 v[74:75], v[74:75], v[102:103], v[78:79]
	v_pk_fma_f32 v[72:73], v[72:73], v[98:99], v[76:77]
	s_nop 0
	v_cvt_pk_bf16_f32 v72, v72, v73
	v_cvt_pk_bf16_f32 v73, v74, v75
	global_store_dwordx2 v[96:97], v[72:73], off offset:512
	v_pk_mul_f32 v[72:73], v[70:71], v[100:101] op_sel_hi:[1,0]
	v_pk_mul_f32 v[74:75], v[68:69], v[100:101] op_sel_hi:[1,0]
	v_mov_b64_e32 v[68:69], v[140:141]
	v_mov_b64_e32 v[70:71], v[142:143]
	v_pk_mul_f32 v[76:77], v[68:69], v[74:75]
	v_pk_mul_f32 v[78:79], v[70:71], v[72:73]
	v_mov_b64_e32 v[68:69], v[144:145]
	v_mov_b64_e32 v[70:71], v[146:147]
	v_mov_b64_e32 v[72:73], v[164:165]
	v_mov_b64_e32 v[74:75], v[166:167]
	v_pk_add_f32 v[70:71], v[70:71], 1.0 op_sel_hi:[1,0]
	v_pk_add_f32 v[68:69], v[68:69], 1.0 op_sel_hi:[1,0]
	v_pk_fma_f32 v[70:71], v[78:79], v[70:71], v[74:75]
	v_pk_fma_f32 v[68:69], v[76:77], v[68:69], v[72:73]
	v_cvt_pk_bf16_f32 v68, v68, v69
	v_cvt_pk_bf16_f32 v69, v70, v71
	global_store_dwordx2 v[96:97], v[68:69], off offset:1024
	v_pk_mul_f32 v[68:69], v[66:67], v[100:101] op_sel_hi:[1,0]
	v_pk_mul_f32 v[70:71], v[64:65], v[100:101] op_sel_hi:[1,0]
	v_mov_b64_e32 v[64:65], v[168:169]
	v_mov_b64_e32 v[66:67], v[170:171]
	v_pk_mul_f32 v[72:73], v[70:71], v[64:65]
	v_pk_mul_f32 v[74:75], v[68:69], v[66:67]
	v_mov_b64_e32 v[64:65], v[172:173]
	v_mov_b64_e32 v[66:67], v[174:175]
	v_mov_b64_e32 v[68:69], v[176:177]
	v_mov_b64_e32 v[70:71], v[178:179]
	v_pk_add_f32 v[66:67], v[66:67], 1.0 op_sel_hi:[1,0]
	v_pk_add_f32 v[64:65], v[64:65], 1.0 op_sel_hi:[1,0]
	v_pk_fma_f32 v[66:67], v[74:75], v[66:67], v[70:71]
	v_pk_fma_f32 v[64:65], v[72:73], v[64:65], v[68:69]
	v_cvt_pk_bf16_f32 v64, v64, v65
	v_cvt_pk_bf16_f32 v65, v66, v67
	global_store_dwordx2 v[96:97], v[64:65], off offset:1536
	v_pk_mul_f32 v[64:65], v[62:63], v[100:101] op_sel_hi:[1,0]
	v_pk_mul_f32 v[66:67], v[60:61], v[100:101] op_sel_hi:[1,0]
	v_mov_b64_e32 v[60:61], v[180:181]
	v_mov_b64_e32 v[62:63], v[182:183]
	v_pk_mul_f32 v[68:69], v[66:67], v[60:61]
	v_pk_mul_f32 v[70:71], v[64:65], v[62:63]
	v_mov_b64_e32 v[60:61], v[184:185]
	v_mov_b64_e32 v[62:63], v[186:187]
	v_mov_b64_e32 v[64:65], v[188:189]
	v_mov_b64_e32 v[66:67], v[190:191]
	v_pk_add_f32 v[62:63], v[62:63], 1.0 op_sel_hi:[1,0]
	v_pk_add_f32 v[60:61], v[60:61], 1.0 op_sel_hi:[1,0]
	v_pk_fma_f32 v[62:63], v[70:71], v[62:63], v[66:67]
	v_pk_fma_f32 v[60:61], v[68:69], v[60:61], v[64:65]
	v_cvt_pk_bf16_f32 v60, v60, v61
	v_cvt_pk_bf16_f32 v61, v62, v63
	global_store_dwordx2 v[96:97], v[60:61], off offset:2048
	v_pk_mul_f32 v[60:61], v[58:59], v[100:101] op_sel_hi:[1,0]
	v_pk_mul_f32 v[62:63], v[56:57], v[100:101] op_sel_hi:[1,0]
	v_mov_b64_e32 v[56:57], v[192:193]
	v_mov_b64_e32 v[58:59], v[194:195]
	v_pk_mul_f32 v[64:65], v[62:63], v[56:57]
	v_pk_mul_f32 v[66:67], v[60:61], v[58:59]
	v_mov_b64_e32 v[56:57], v[196:197]
	v_mov_b64_e32 v[58:59], v[198:199]
	v_mov_b64_e32 v[60:61], v[200:201]
	v_mov_b64_e32 v[62:63], v[202:203]
	v_pk_add_f32 v[58:59], v[58:59], 1.0 op_sel_hi:[1,0]
	v_pk_add_f32 v[56:57], v[56:57], 1.0 op_sel_hi:[1,0]
	v_pk_fma_f32 v[58:59], v[66:67], v[58:59], v[62:63]
	v_pk_fma_f32 v[56:57], v[64:65], v[56:57], v[60:61]
	v_cvt_pk_bf16_f32 v56, v56, v57
	v_cvt_pk_bf16_f32 v57, v58, v59
	global_store_dwordx2 v[96:97], v[56:57], off offset:2560
	v_pk_mul_f32 v[56:57], v[54:55], v[100:101] op_sel_hi:[1,0]
	v_pk_mul_f32 v[58:59], v[52:53], v[100:101] op_sel_hi:[1,0]
	v_mov_b64_e32 v[52:53], v[204:205]
	v_mov_b64_e32 v[54:55], v[206:207]
	v_pk_mul_f32 v[60:61], v[58:59], v[52:53]
	v_pk_mul_f32 v[62:63], v[56:57], v[54:55]
	v_mov_b64_e32 v[52:53], v[208:209]
	v_mov_b64_e32 v[54:55], v[210:211]
	v_mov_b64_e32 v[56:57], v[212:213]
	v_mov_b64_e32 v[58:59], v[214:215]
	v_pk_add_f32 v[54:55], v[54:55], 1.0 op_sel_hi:[1,0]
	v_pk_add_f32 v[52:53], v[52:53], 1.0 op_sel_hi:[1,0]
	v_pk_fma_f32 v[54:55], v[62:63], v[54:55], v[58:59]
	v_pk_fma_f32 v[52:53], v[60:61], v[52:53], v[56:57]
	v_pk_mul_f32 v[58:59], v[48:49], v[100:101] op_sel_hi:[1,0]
	v_cvt_pk_bf16_f32 v48, v52, v53
	v_cvt_pk_bf16_f32 v49, v54, v55
	global_store_dwordx2 v[96:97], v[48:49], off offset:3072
	v_pk_mul_f32 v[56:57], v[50:51], v[100:101] op_sel_hi:[1,0]
	v_mov_b64_e32 v[48:49], v[216:217]
	v_mov_b64_e32 v[50:51], v[218:219]
	v_pk_mul_f32 v[58:59], v[58:59], v[48:49]
	v_pk_mul_f32 v[56:57], v[56:57], v[50:51]
	v_mov_b64_e32 v[48:49], v[220:221]
	v_mov_b64_e32 v[50:51], v[222:223]
	v_mov_b64_e32 v[52:53], v[224:225]
	v_mov_b64_e32 v[54:55], v[226:227]
	v_pk_add_f32 v[50:51], v[50:51], 1.0 op_sel_hi:[1,0]
	v_pk_add_f32 v[48:49], v[48:49], 1.0 op_sel_hi:[1,0]
	v_pk_fma_f32 v[50:51], v[56:57], v[50:51], v[54:55]
	v_pk_fma_f32 v[48:49], v[58:59], v[48:49], v[52:53]
	v_cvt_pk_bf16_f32 v48, v48, v49
	v_cvt_pk_bf16_f32 v49, v50, v51
	global_store_dwordx2 v[96:97], v[48:49], off offset:3584
	s_waitcnt vmcnt(8)
	v_lshlrev_b32_e32 v76, 16, v4
	v_and_b32_e32 v77, 0xffff0000, v4
	v_lshlrev_b32_e32 v78, 16, v5
	v_and_b32_e32 v79, 0xffff0000, v5
	v_lshlrev_b32_e32 v72, 16, v8
	v_and_b32_e32 v73, 0xffff0000, v8
	v_lshlrev_b32_e32 v74, 16, v9
	v_and_b32_e32 v75, 0xffff0000, v9
	v_lshlrev_b32_e32 v68, 16, v12
	v_and_b32_e32 v69, 0xffff0000, v12
	v_lshlrev_b32_e32 v70, 16, v13
	v_and_b32_e32 v71, 0xffff0000, v13
	v_lshlrev_b32_e32 v64, 16, v16
	v_and_b32_e32 v65, 0xffff0000, v16
	v_lshlrev_b32_e32 v66, 16, v17
	v_and_b32_e32 v67, 0xffff0000, v17
	v_lshlrev_b32_e32 v60, 16, v20
	v_and_b32_e32 v61, 0xffff0000, v20
	v_lshlrev_b32_e32 v62, 16, v21
	v_and_b32_e32 v63, 0xffff0000, v21
	v_lshlrev_b32_e32 v56, 16, v24
	v_and_b32_e32 v57, 0xffff0000, v24
	v_lshlrev_b32_e32 v58, 16, v25
	v_and_b32_e32 v59, 0xffff0000, v25
	v_lshlrev_b32_e32 v52, 16, v28
	v_and_b32_e32 v53, 0xffff0000, v28
	v_lshlrev_b32_e32 v54, 16, v29
	v_and_b32_e32 v55, 0xffff0000, v29
	v_lshlrev_b32_e32 v48, 16, v148
	v_and_b32_e32 v49, 0xffff0000, v148
	v_lshlrev_b32_e32 v50, 16, v149
	v_and_b32_e32 v51, 0xffff0000, v149
	v_mov_b64_e32 v[4:5], v[232:233]
	v_mov_b64_e32 v[8:9], v[234:235]
	v_mov_b64_e32 v[12:13], v[236:237]
	v_mov_b64_e32 v[16:17], v[238:239]
	v_mov_b64_e32 v[20:21], v[240:241]
	v_mov_b64_e32 v[24:25], v[242:243]
	v_mov_b64_e32 v[28:29], v[244:245]
	v_mov_b64_e32 v[148:149], v[246:247]
	v_mov_b64_e32 v[232:233], v[248:249]
	v_mov_b64_e32 v[234:235], v[250:251]
	v_mov_b64_e32 v[236:237], v[252:253]
	v_mov_b64_e32 v[238:239], v[254:255]
	v_mov_b64_e32 v[240:241], v[150:151]
	v_mov_b64_e32 v[242:243], v[152:153]
	v_mov_b64_e32 v[244:245], v[154:155]
	v_mov_b64_e32 v[246:247], v[156:157]
	s_cbranch_vccnz .LBB0_502

.Lnorm3_skip_1068:
	v_mov_b32_e32 v98, v73
	v_mov_b32_e32 v99, v77
	v_mov_b32_e32 v96, v72
	v_mov_b32_e32 v97, v76
	v_pk_mul_f32 v[98:99], v[98:99], v[98:99]
	v_mov_b32_e32 v100, v75
	v_mov_b32_e32 v101, v79
	v_pk_fma_f32 v[96:97], v[96:97], v[96:97], v[98:99]
	v_mov_b32_e32 v98, v74
	v_mov_b32_e32 v99, v78
	v_pk_mul_f32 v[100:101], v[100:101], v[100:101]
	s_nop 0
	v_pk_fma_f32 v[98:99], v[98:99], v[98:99], v[100:101]
	v_pk_mul_f32 v[100:101], v[68:69], v[68:69]
	v_pk_add_f32 v[96:97], v[96:97], v[98:99]
	v_pk_mul_f32 v[98:99], v[70:71], v[70:71]
	v_pk_add_f32 v[96:97], v[96:97], v[96:97] op_sel_hi:[0,1]
	v_pk_mov_b32 v[102:103], v[100:101], v[98:99] op_sel:[1,0]
	v_mov_b32_e32 v101, v99
	v_pk_add_f32 v[98:99], v[102:103], v[100:101]
	v_mul_f32_e32 v100, v64, v64
	v_pk_fma_f32 v[100:101], v[64:65], v[64:65], v[100:101] op_sel_hi:[1,1,0]
	v_pk_add_f32 v[98:99], v[98:99], v[98:99] op_sel_hi:[0,1]
	v_mul_f32_e32 v100, v66, v66
	v_pk_fma_f32 v[102:103], v[66:67], v[66:67], v[100:101] op_sel_hi:[1,1,0]
	v_mul_f32_e32 v100, v60, v60
	v_mul_f32_e32 v102, v61, v61
	v_mul_f32_e32 v98, v62, v62
	v_mul_f32_e32 v96, v63, v63
	v_pk_add_f32 v[100:101], v[100:101], v[102:103]
	v_pk_add_f32 v[96:97], v[98:99], v[96:97]
	v_pk_mul_f32 v[98:99], v[58:59], v[58:59]
	v_pk_add_f32 v[96:97], v[100:101], v[96:97]
	v_pk_mul_f32 v[100:101], v[56:57], v[56:57]
	v_pk_add_f32 v[96:97], v[96:97], v[96:97] op_sel_hi:[0,1]
	v_pk_mov_b32 v[102:103], v[100:101], v[98:99] op_sel:[1,0]
	v_mov_b32_e32 v101, v99
	v_pk_add_f32 v[98:99], v[102:103], v[100:101]
	v_mul_f32_e32 v100, v52, v52
	v_pk_fma_f32 v[100:101], v[52:53], v[52:53], v[100:101] op_sel_hi:[1,1,0]
	v_pk_add_f32 v[98:99], v[98:99], v[98:99] op_sel_hi:[0,1]
	v_mul_f32_e32 v100, v54, v54
	v_pk_fma_f32 v[102:103], v[54:55], v[54:55], v[100:101] op_sel_hi:[1,1,0]
	v_mul_f32_e32 v100, v48, v48
	v_mul_f32_e32 v102, v49, v49
	v_mul_f32_e32 v98, v50, v50
	v_mul_f32_e32 v96, v51, v51
	v_pk_add_f32 v[100:101], v[100:101], v[102:103]
	v_pk_add_f32 v[96:97], v[98:99], v[96:97]
	s_nop 0
	v_pk_add_f32 v[96:97], v[100:101], v[96:97]
	s_nop 0
	v_add_f32_e32 v95, v96, v97
	ds_bpermute_b32 v96, v1, v95
	s_waitcnt lgkmcnt(0)
	v_add_f32_e32 v95, v95, v96
	ds_bpermute_b32 v96, v80, v95
	s_waitcnt lgkmcnt(0)
	v_add_f32_e32 v95, v95, v96
	ds_bpermute_b32 v96, v81, v95
	s_waitcnt lgkmcnt(0)
	v_add_f32_e32 v95, v95, v96
	ds_bpermute_b32 v96, v82, v95
	s_waitcnt lgkmcnt(0)
	v_add_f32_e32 v95, v95, v96
	ds_bpermute_b32 v96, v83, v95
	s_waitcnt lgkmcnt(0)
	v_add_f32_e32 v95, v95, v96
	ds_bpermute_b32 v96, v84, v95
	s_waitcnt lgkmcnt(0)
	v_add_f32_e32 v95, v95, v96
	v_fmamk_f32 v95, v95, 0x3a000000, v85
	v_mul_f32_e32 v96, 0x4f800000, v95
	v_cmp_gt_f32_e32 vcc, s33, v95
	s_nop 1
	v_cndmask_b32_e32 v95, v95, v96, vcc
	v_sqrt_f32_e32 v96, v95
	s_nop 0
	v_add_u32_e32 v97, -1, v96
	v_fma_f32 v98, -v97, v96, v95
	v_cmp_ge_f32_e64 s[6:7], 0, v98
	v_add_u32_e32 v98, 1, v96
	s_nop 0
	v_cndmask_b32_e64 v97, v96, v97, s[6:7]
	v_fma_f32 v96, -v98, v96, v95
	v_cmp_lt_f32_e64 s[6:7], 0, v96
	s_nop 1
	v_cndmask_b32_e64 v96, v97, v98, s[6:7]
	v_mul_f32_e32 v97, 0x37800000, v96
	v_cndmask_b32_e32 v96, v96, v97, vcc
	v_cmp_class_f32_e32 vcc, v95, v86
	s_nop 1
	v_cndmask_b32_e32 v95, v96, v95, vcc
	v_div_scale_f32 v96, s[6:7], v95, v95, 1.0
	v_rcp_f32_e32 v97, v96
	s_ashr_i32 s6, s12, 11
	s_mul_hi_i32 s7, s6, 0x12000
	s_mul_i32 s6, s6, 0x12000
	v_fma_f32 v98, -v96, v97, 1.0
	v_fmac_f32_e32 v97, v98, v97
	v_div_scale_f32 v98, vcc, 1.0, v95, 1.0
	v_mul_f32_e32 v99, v98, v97
	v_fma_f32 v100, -v96, v99, v98
	v_fmac_f32_e32 v99, v100, v97
	v_fma_f32 v96, -v96, v99, v98
	v_div_fmas_f32 v96, v96, v97, v99
	v_div_fixup_f32 v100, v96, v95, 1.0
	v_pk_mul_f32 v[96:97], v[78:79], v[100:101] op_sel_hi:[1,0]
	v_pk_mul_f32 v[98:99], v[76:77], v[100:101] op_sel_hi:[1,0]
	s_waitcnt vmcnt(24)
	v_mov_b64_e32 v[76:77], v[116:117]
	v_mov_b64_e32 v[78:79], v[118:119]
	s_add_u32 s6, s28, s6
	s_addc_u32 s7, s29, s7
	s_add_u32 s18, s6, 0x2000
	s_addc_u32 s19, s7, 0
	s_ashr_i32 s13, s12, 31
	s_lshl_b64 s[12:13], s[12:13], 12
	s_add_i32 s31, s31, s22
	s_add_i32 s21, s21, 1
	s_and_b64 vcc, exec, s[16:17]
	s_waitcnt vmcnt(24)
	v_pk_mul_f32 v[102:103], v[76:77], v[98:99]
	v_pk_mul_f32 v[104:105], v[78:79], v[96:97]
	v_mov_b64_e32 v[76:77], v[120:121]
	v_mov_b64_e32 v[78:79], v[122:123]
	v_mov_b64_e32 v[96:97], v[124:125]
	v_mov_b64_e32 v[98:99], v[126:127]
	v_pk_add_f32 v[78:79], v[78:79], 1.0 op_sel_hi:[1,0]
	v_pk_add_f32 v[76:77], v[76:77], 1.0 op_sel_hi:[1,0]
	v_pk_fma_f32 v[78:79], v[78:79], v[104:105], v[98:99]
	v_pk_fma_f32 v[76:77], v[76:77], v[102:103], v[96:97]
	v_lshl_add_u64 v[96:97], v[46:47], 0, s[12:13]
	v_cvt_pk_bf16_f32 v76, v76, v77
	v_cvt_pk_bf16_f32 v77, v78, v79
	global_store_dwordx2 v[96:97], v[76:77], off
	v_pk_mul_f32 v[76:77], v[74:75], v[100:101] op_sel_hi:[1,0]
	v_pk_mul_f32 v[78:79], v[72:73], v[100:101] op_sel_hi:[1,0]
	v_mov_b64_e32 v[72:73], v[128:129]
	v_mov_b64_e32 v[74:75], v[130:131]
	s_mov_b32 s12, s14
	v_pk_mul_f32 v[98:99], v[72:73], v[78:79]
	v_pk_mul_f32 v[102:103], v[74:75], v[76:77]
	v_mov_b64_e32 v[72:73], v[132:133]
	v_mov_b64_e32 v[74:75], v[134:135]
	v_mov_b64_e32 v[76:77], v[136:137]
	v_mov_b64_e32 v[78:79], v[138:139]
	v_pk_add_f32 v[74:75], v[74:75], 1.0 op_sel_hi:[1,0]
	v_pk_add_f32 v[72:73], v[72:73], 1.0 op_sel_hi:[1,0]
	v_pk_fma_f32 v[74:75], v[74:75], v[102:103], v[78:79]
	v_pk_fma_f32 v[72:73], v[72:73], v[98:99], v[76:77]
	s_nop 0
	v_cvt_pk_bf16_f32 v72, v72, v73
	v_cvt_pk_bf16_f32 v73, v74, v75
	global_store_dwordx2 v[96:97], v[72:73], off offset:512
	v_pk_mul_f32 v[72:73], v[70:71], v[100:101] op_sel_hi:[1,0]
	v_pk_mul_f32 v[74:75], v[68:69], v[100:101] op_sel_hi:[1,0]
	v_mov_b64_e32 v[68:69], v[140:141]
	v_mov_b64_e32 v[70:71], v[142:143]
	v_pk_mul_f32 v[76:77], v[68:69], v[74:75]
	v_pk_mul_f32 v[78:79], v[70:71], v[72:73]
	v_mov_b64_e32 v[68:69], v[144:145]
	v_mov_b64_e32 v[70:71], v[146:147]
	v_mov_b64_e32 v[72:73], v[164:165]
	v_mov_b64_e32 v[74:75], v[166:167]
	v_pk_add_f32 v[70:71], v[70:71], 1.0 op_sel_hi:[1,0]
	v_pk_add_f32 v[68:69], v[68:69], 1.0 op_sel_hi:[1,0]
	v_pk_fma_f32 v[70:71], v[78:79], v[70:71], v[74:75]
	v_pk_fma_f32 v[68:69], v[76:77], v[68:69], v[72:73]
	v_cvt_pk_bf16_f32 v68, v68, v69
	v_cvt_pk_bf16_f32 v69, v70, v71
	global_store_dwordx2 v[96:97], v[68:69], off offset:1024
	v_pk_mul_f32 v[68:69], v[66:67], v[100:101] op_sel_hi:[1,0]
	v_pk_mul_f32 v[70:71], v[64:65], v[100:101] op_sel_hi:[1,0]
	v_mov_b64_e32 v[64:65], v[168:169]
	v_mov_b64_e32 v[66:67], v[170:171]
	v_pk_mul_f32 v[72:73], v[70:71], v[64:65]
	v_pk_mul_f32 v[74:75], v[68:69], v[66:67]
	v_mov_b64_e32 v[64:65], v[172:173]
	v_mov_b64_e32 v[66:67], v[174:175]
	v_mov_b64_e32 v[68:69], v[176:177]
	v_mov_b64_e32 v[70:71], v[178:179]
	v_pk_add_f32 v[66:67], v[66:67], 1.0 op_sel_hi:[1,0]
	v_pk_add_f32 v[64:65], v[64:65], 1.0 op_sel_hi:[1,0]
	v_pk_fma_f32 v[66:67], v[74:75], v[66:67], v[70:71]
	v_pk_fma_f32 v[64:65], v[72:73], v[64:65], v[68:69]
	v_cvt_pk_bf16_f32 v64, v64, v65
	v_cvt_pk_bf16_f32 v65, v66, v67
	global_store_dwordx2 v[96:97], v[64:65], off offset:1536
	v_pk_mul_f32 v[64:65], v[62:63], v[100:101] op_sel_hi:[1,0]
	v_pk_mul_f32 v[66:67], v[60:61], v[100:101] op_sel_hi:[1,0]
	v_mov_b64_e32 v[60:61], v[180:181]
	v_mov_b64_e32 v[62:63], v[182:183]
	v_pk_mul_f32 v[68:69], v[66:67], v[60:61]
	v_pk_mul_f32 v[70:71], v[64:65], v[62:63]
	v_mov_b64_e32 v[60:61], v[184:185]
	v_mov_b64_e32 v[62:63], v[186:187]
	v_mov_b64_e32 v[64:65], v[188:189]
	v_mov_b64_e32 v[66:67], v[190:191]
	v_pk_add_f32 v[62:63], v[62:63], 1.0 op_sel_hi:[1,0]
	v_pk_add_f32 v[60:61], v[60:61], 1.0 op_sel_hi:[1,0]
	v_pk_fma_f32 v[62:63], v[70:71], v[62:63], v[66:67]
	v_pk_fma_f32 v[60:61], v[68:69], v[60:61], v[64:65]
	v_cvt_pk_bf16_f32 v60, v60, v61
	v_cvt_pk_bf16_f32 v61, v62, v63
	global_store_dwordx2 v[96:97], v[60:61], off offset:2048
	v_pk_mul_f32 v[60:61], v[58:59], v[100:101] op_sel_hi:[1,0]
	v_pk_mul_f32 v[62:63], v[56:57], v[100:101] op_sel_hi:[1,0]
	v_mov_b64_e32 v[56:57], v[192:193]
	v_mov_b64_e32 v[58:59], v[194:195]
	v_pk_mul_f32 v[64:65], v[62:63], v[56:57]
	v_pk_mul_f32 v[66:67], v[60:61], v[58:59]
	v_mov_b64_e32 v[56:57], v[196:197]
	v_mov_b64_e32 v[58:59], v[198:199]
	v_mov_b64_e32 v[60:61], v[200:201]
	v_mov_b64_e32 v[62:63], v[202:203]
	v_pk_add_f32 v[58:59], v[58:59], 1.0 op_sel_hi:[1,0]
	v_pk_add_f32 v[56:57], v[56:57], 1.0 op_sel_hi:[1,0]
	v_pk_fma_f32 v[58:59], v[66:67], v[58:59], v[62:63]
	v_pk_fma_f32 v[56:57], v[64:65], v[56:57], v[60:61]
	v_cvt_pk_bf16_f32 v56, v56, v57
	v_cvt_pk_bf16_f32 v57, v58, v59
	global_store_dwordx2 v[96:97], v[56:57], off offset:2560
	v_pk_mul_f32 v[56:57], v[54:55], v[100:101] op_sel_hi:[1,0]
	v_pk_mul_f32 v[58:59], v[52:53], v[100:101] op_sel_hi:[1,0]
	v_mov_b64_e32 v[52:53], v[204:205]
	v_mov_b64_e32 v[54:55], v[206:207]
	v_pk_mul_f32 v[60:61], v[58:59], v[52:53]
	v_pk_mul_f32 v[62:63], v[56:57], v[54:55]
	v_mov_b64_e32 v[52:53], v[208:209]
	v_mov_b64_e32 v[54:55], v[210:211]
	v_mov_b64_e32 v[56:57], v[212:213]
	v_mov_b64_e32 v[58:59], v[214:215]
	v_pk_add_f32 v[54:55], v[54:55], 1.0 op_sel_hi:[1,0]
	v_pk_add_f32 v[52:53], v[52:53], 1.0 op_sel_hi:[1,0]
	v_pk_fma_f32 v[54:55], v[62:63], v[54:55], v[58:59]
	v_pk_fma_f32 v[52:53], v[60:61], v[52:53], v[56:57]
	v_pk_mul_f32 v[58:59], v[48:49], v[100:101] op_sel_hi:[1,0]
	v_cvt_pk_bf16_f32 v48, v52, v53
	v_cvt_pk_bf16_f32 v49, v54, v55
	global_store_dwordx2 v[96:97], v[48:49], off offset:3072
	v_pk_mul_f32 v[56:57], v[50:51], v[100:101] op_sel_hi:[1,0]
	v_mov_b64_e32 v[48:49], v[216:217]
	v_mov_b64_e32 v[50:51], v[218:219]
	v_pk_mul_f32 v[58:59], v[58:59], v[48:49]
	v_pk_mul_f32 v[56:57], v[56:57], v[50:51]
	v_mov_b64_e32 v[48:49], v[220:221]
	v_mov_b64_e32 v[50:51], v[222:223]
	v_mov_b64_e32 v[52:53], v[224:225]
	v_mov_b64_e32 v[54:55], v[226:227]
	v_pk_add_f32 v[50:51], v[50:51], 1.0 op_sel_hi:[1,0]
	v_pk_add_f32 v[48:49], v[48:49], 1.0 op_sel_hi:[1,0]
	v_pk_fma_f32 v[50:51], v[56:57], v[50:51], v[54:55]
	v_pk_fma_f32 v[48:49], v[58:59], v[48:49], v[52:53]
	v_cvt_pk_bf16_f32 v48, v48, v49
	v_cvt_pk_bf16_f32 v49, v50, v51
	global_store_dwordx2 v[96:97], v[48:49], off offset:3584
	s_waitcnt vmcnt(8)
	v_lshlrev_b32_e32 v76, 16, v4
	v_and_b32_e32 v77, 0xffff0000, v4
	v_lshlrev_b32_e32 v78, 16, v5
	v_and_b32_e32 v79, 0xffff0000, v5
	v_lshlrev_b32_e32 v72, 16, v8
	v_and_b32_e32 v73, 0xffff0000, v8
	v_lshlrev_b32_e32 v74, 16, v9
	v_and_b32_e32 v75, 0xffff0000, v9
	v_lshlrev_b32_e32 v68, 16, v12
	v_and_b32_e32 v69, 0xffff0000, v12
	v_lshlrev_b32_e32 v70, 16, v13
	v_and_b32_e32 v71, 0xffff0000, v13
	v_lshlrev_b32_e32 v64, 16, v16
	v_and_b32_e32 v65, 0xffff0000, v16
	v_lshlrev_b32_e32 v66, 16, v17
	v_and_b32_e32 v67, 0xffff0000, v17
	v_lshlrev_b32_e32 v60, 16, v20
	v_and_b32_e32 v61, 0xffff0000, v20
	v_lshlrev_b32_e32 v62, 16, v21
	v_and_b32_e32 v63, 0xffff0000, v21
	v_lshlrev_b32_e32 v56, 16, v24
	v_and_b32_e32 v57, 0xffff0000, v24
	v_lshlrev_b32_e32 v58, 16, v25
	v_and_b32_e32 v59, 0xffff0000, v25
	v_lshlrev_b32_e32 v52, 16, v28
	v_and_b32_e32 v53, 0xffff0000, v28
	v_lshlrev_b32_e32 v54, 16, v29
	v_and_b32_e32 v55, 0xffff0000, v29
	v_lshlrev_b32_e32 v48, 16, v148
	v_and_b32_e32 v49, 0xffff0000, v148
	v_lshlrev_b32_e32 v50, 16, v149
	v_and_b32_e32 v51, 0xffff0000, v149
	v_mov_b64_e32 v[4:5], v[232:233]
	v_mov_b64_e32 v[8:9], v[234:235]
	v_mov_b64_e32 v[12:13], v[236:237]
	v_mov_b64_e32 v[16:17], v[238:239]
	v_mov_b64_e32 v[20:21], v[240:241]
	v_mov_b64_e32 v[24:25], v[242:243]
	v_mov_b64_e32 v[28:29], v[244:245]
	v_mov_b64_e32 v[148:149], v[246:247]
	v_mov_b64_e32 v[232:233], v[248:249]
	v_mov_b64_e32 v[234:235], v[250:251]
	v_mov_b64_e32 v[236:237], v[252:253]
	v_mov_b64_e32 v[238:239], v[254:255]
	v_mov_b64_e32 v[240:241], v[150:151]
	v_mov_b64_e32 v[242:243], v[152:153]
	v_mov_b64_e32 v[244:245], v[154:155]
	v_mov_b64_e32 v[246:247], v[156:157]
	s_cbranch_vccnz .LBB0_1073
